# poolconv phase: UG loads with default policy instead of nt (halo rows are re-read by neighbouring waves), policy sweep on top of v70
# speedup vs baseline: 1.0428x; 1.0036x over previous
; __device__ __forceinline__ void pc_pass(int Q, const bf16* UG, bf16* A2, const float* cw, const float* cbias, LAS float* Yw, int mt, int ts, int lane) {
;     ...
;     for (int i = 0; i < 38; ++i) { const int t = ts - 30 + i; graw[i] = (t >= 0) ? __builtin_nontemporal_load((const unsigned*)(UG + (size_t)(mt - 30 + i) * 1024 + 512 + c0)) : 0u; }
.LBB0_141:
	v_mov_b32_e32 v211, v147
	v_readlane_b32 s12, v253, 35
	v_readlane_b32 s13, v253, 36
	v_lshl_add_u32 v120, v211, 1, s33
	v_ashrrev_i32_e32 v121, 31, v120
	v_mov_b32_e32 v213, 0
	s_andn2_b64 vcc, exec, s[12:13]
	v_mov_b32_e32 v212, 0
	s_cbranch_vccnz .LBB0_143
	v_readlane_b32 s12, v253, 37
	v_readlane_b32 s13, v253, 38
	s_nop 1
	v_lshl_add_u64 v[56:57], v[120:121], 1, s[12:13]
	global_load_dword v212, v[56:57], off offset:1024
.LBB0_143:
	v_readlane_b32 s12, v253, 39
	v_readlane_b32 s13, v253, 40
	s_andn2_b64 vcc, exec, s[12:13]
	s_cbranch_vccnz .LBB0_179
	v_readlane_b32 s12, v253, 41
	v_readlane_b32 s13, v253, 42
	s_nop 1
	v_lshl_add_u64 v[56:57], v[120:121], 1, s[12:13]
	global_load_dword v213, v[56:57], off offset:1024
	v_mov_b32_e32 v215, 0
	s_andn2_b64 vcc, exec, s[72:73]
	v_mov_b32_e32 v214, 0
	s_cbranch_vccz .LBB0_180

; __device__ __forceinline__ void pc_pass(int Q, const bf16* UG, bf16* A2, const float* cw, const float* cbias, LAS float* Yw, int mt, int ts, int lane) {
;     ...
;     for (int i = 0; i < 38; ++i) { const int t = ts - 30 + i; graw[i] = (t >= 0) ? __builtin_nontemporal_load((const unsigned*)(UG + (size_t)(mt - 30 + i) * 1024 + 512 + c0)) : 0u; }
.LBB0_146:
	v_readlane_b32 s12, v253, 45
	v_readlane_b32 s13, v253, 46
	s_nop 1
	v_lshl_add_u64 v[56:57], v[120:121], 1, s[12:13]
	global_load_dword v215, v[56:57], off offset:1024
	v_mov_b32_e32 v217, 0
	s_andn2_b64 vcc, exec, s[92:93]
	v_mov_b32_e32 v216, 0
	s_cbranch_vccz .LBB0_182

; __device__ __forceinline__ void pc_pass(int Q, const bf16* UG, bf16* A2, const float* cw, const float* cbias, LAS float* Yw, int mt, int ts, int lane) {
;     ...
;     for (int i = 0; i < 38; ++i) { const int t = ts - 30 + i; graw[i] = (t >= 0) ? __builtin_nontemporal_load((const unsigned*)(UG + (size_t)(mt - 30 + i) * 1024 + 512 + c0)) : 0u; }
.LBB0_148:
	v_readlane_b32 s12, v253, 49
	v_readlane_b32 s13, v253, 50
	s_nop 1
	v_lshl_add_u64 v[56:57], v[120:121], 1, s[12:13]
	global_load_dword v217, v[56:57], off offset:1024
	v_mov_b32_e32 v191, 0
	s_andn2_b64 vcc, exec, s[8:9]
	v_mov_b32_e32 v218, 0
	s_cbranch_vccz .LBB0_184

; __device__ __forceinline__ void pc_pass(int Q, const bf16* UG, bf16* A2, const float* cw, const float* cbias, LAS float* Yw, int mt, int ts, int lane) {
;     ...
;     for (int i = 0; i < 38; ++i) { const int t = ts - 30 + i; graw[i] = (t >= 0) ? __builtin_nontemporal_load((const unsigned*)(UG + (size_t)(mt - 30 + i) * 1024 + 512 + c0)) : 0u; }
.LBB0_150:
	v_readlane_b32 s12, v253, 53
	v_readlane_b32 s13, v253, 54
	s_nop 1
	v_lshl_add_u64 v[56:57], v[120:121], 1, s[12:13]
	global_load_dword v191, v[56:57], off offset:1024
	v_mov_b32_e32 v187, 0
	s_andn2_b64 vcc, exec, s[54:55]
	v_mov_b32_e32 v189, 0
	s_cbranch_vccz .LBB0_186

; __device__ __forceinline__ void pc_pass(int Q, const bf16* UG, bf16* A2, const float* cw, const float* cbias, LAS float* Yw, int mt, int ts, int lane) {
;     ...
;     for (int i = 0; i < 38; ++i) { const int t = ts - 30 + i; graw[i] = (t >= 0) ? __builtin_nontemporal_load((const unsigned*)(UG + (size_t)(mt - 30 + i) * 1024 + 512 + c0)) : 0u; }
.LBB0_152:
	v_readlane_b32 s12, v253, 57
	v_readlane_b32 s13, v253, 58
	s_nop 1
	v_lshl_add_u64 v[56:57], v[120:121], 1, s[12:13]
	global_load_dword v187, v[56:57], off offset:1024
	v_mov_b32_e32 v183, 0
	s_andn2_b64 vcc, exec, s[96:97]
	v_mov_b32_e32 v185, 0
	s_cbranch_vccz .LBB0_188

; __device__ __forceinline__ void pc_pass(int Q, const bf16* UG, bf16* A2, const float* cw, const float* cbias, LAS float* Yw, int mt, int ts, int lane) {
;     ...
;     for (int i = 0; i < 38; ++i) { const int t = ts - 30 + i; graw[i] = (t >= 0) ? __builtin_nontemporal_load((const unsigned*)(UG + (size_t)(mt - 30 + i) * 1024 + 512 + c0)) : 0u; }
.LBB0_154:
	v_readlane_b32 s12, v253, 61
	v_readlane_b32 s13, v253, 62
	s_nop 1
	v_lshl_add_u64 v[56:57], v[120:121], 1, s[12:13]
	global_load_dword v183, v[56:57], off offset:1024
	v_mov_b32_e32 v177, 0
	s_andn2_b64 vcc, exec, s[56:57]
	v_mov_b32_e32 v179, 0
	s_cbranch_vccz .LBB0_190

; __device__ __forceinline__ void pc_pass(int Q, const bf16* UG, bf16* A2, const float* cw, const float* cbias, LAS float* Yw, int mt, int ts, int lane) {
;     ...
;     for (int i = 0; i < 38; ++i) { const int t = ts - 30 + i; graw[i] = (t >= 0) ? __builtin_nontemporal_load((const unsigned*)(UG + (size_t)(mt - 30 + i) * 1024 + 512 + c0)) : 0u; }
.LBB0_156:
	v_readlane_b32 s12, v254, 1
	v_readlane_b32 s13, v254, 2
	s_nop 1
	v_lshl_add_u64 v[56:57], v[120:121], 1, s[12:13]
	global_load_dword v177, v[56:57], off offset:1024
	v_mov_b32_e32 v173, 0
	s_andn2_b64 vcc, exec, s[46:47]
	v_mov_b32_e32 v175, 0
	s_cbranch_vccz .LBB0_192

; __device__ __forceinline__ void pc_pass(int Q, const bf16* UG, bf16* A2, const float* cw, const float* cbias, LAS float* Yw, int mt, int ts, int lane) {
;     ...
;     for (int i = 0; i < 38; ++i) { const int t = ts - 30 + i; graw[i] = (t >= 0) ? __builtin_nontemporal_load((const unsigned*)(UG + (size_t)(mt - 30 + i) * 1024 + 512 + c0)) : 0u; }
.LBB0_158:
	v_readlane_b32 s12, v254, 7
	v_readlane_b32 s13, v254, 8
	s_nop 1
	v_lshl_add_u64 v[56:57], v[120:121], 1, s[12:13]
	global_load_dword v173, v[56:57], off offset:1024
.LBB0_159:
	v_cndmask_b32_e64 v56, 0, 1, s[42:43]
	v_mov_b32_e32 v169, 0
	v_cmp_ne_u32_e64 s[16:17], 1, v56
	s_andn2_b64 vcc, exec, s[42:43]
	v_mov_b32_e32 v171, 0
	s_cbranch_vccnz .LBB0_161
	v_readlane_b32 s12, v254, 11
	v_readlane_b32 s13, v254, 12
	s_nop 1
	v_lshl_add_u64 v[56:57], v[120:121], 1, s[12:13]
	global_load_dword v171, v[56:57], off offset:1024
.LBB0_161:
	v_cndmask_b32_e64 v56, 0, 1, s[6:7]
	v_cmp_ne_u32_e64 s[18:19], 1, v56
	s_andn2_b64 vcc, exec, s[6:7]
	s_cbranch_vccnz .LBB0_163
	v_readlane_b32 s12, v254, 15
	v_readlane_b32 s13, v254, 16
	s_nop 1
	v_lshl_add_u64 v[56:57], v[120:121], 1, s[12:13]
	global_load_dword v169, v[56:57], off offset:1024
.LBB0_163:
	v_cndmask_b32_e64 v56, 0, 1, s[44:45]
	v_mov_b32_e32 v163, 0
	v_cmp_ne_u32_e64 s[20:21], 1, v56
	s_andn2_b64 vcc, exec, s[44:45]
	v_mov_b32_e32 v165, 0
	s_cbranch_vccnz .LBB0_165
	v_readlane_b32 s12, v254, 19
	v_readlane_b32 s13, v254, 20
	s_nop 1
	v_lshl_add_u64 v[56:57], v[120:121], 1, s[12:13]
	global_load_dword v165, v[56:57], off offset:1024
.LBB0_165:
	v_cndmask_b32_e64 v56, 0, 1, s[0:1]
	v_cmp_ne_u32_e64 s[22:23], 1, v56
	s_andn2_b64 vcc, exec, s[0:1]
	s_cbranch_vccnz .LBB0_167
	v_readlane_b32 s12, v254, 23
	v_readlane_b32 s13, v254, 24
	s_nop 1
	v_lshl_add_u64 v[56:57], v[120:121], 1, s[12:13]
	global_load_dword v163, v[56:57], off offset:1024
.LBB0_167:
	v_cndmask_b32_e64 v56, 0, 1, s[82:83]
	v_mov_b32_e32 v141, 0
	v_cmp_ne_u32_e64 s[24:25], 1, v56
	s_andn2_b64 vcc, exec, s[82:83]
	v_mov_b32_e32 v143, 0
	s_cbranch_vccnz .LBB0_169
	v_readlane_b32 s12, v254, 27
	v_readlane_b32 s13, v254, 28
	s_nop 1
	v_lshl_add_u64 v[56:57], v[120:121], 1, s[12:13]
	global_load_dword v143, v[56:57], off offset:1024
.LBB0_169:
	v_cndmask_b32_e64 v56, 0, 1, s[58:59]
	v_cmp_ne_u32_e64 s[26:27], 1, v56
	s_andn2_b64 vcc, exec, s[58:59]
	s_cbranch_vccnz .LBB0_171
	v_readlane_b32 s12, v254, 31
	v_readlane_b32 s13, v254, 32
	s_nop 1
	v_lshl_add_u64 v[56:57], v[120:121], 1, s[12:13]
	global_load_dword v141, v[56:57], off offset:1024
.LBB0_171:
	v_cndmask_b32_e64 v56, 0, 1, s[48:49]
	v_mov_b32_e32 v137, 0
	v_cmp_ne_u32_e64 s[12:13], 1, v56
	s_andn2_b64 vcc, exec, s[48:49]
	v_mov_b32_e32 v139, 0
	s_cbranch_vccnz .LBB0_193
	v_readlane_b32 vcc_lo, v254, 35
	v_readlane_b32 vcc_hi, v254, 36
	s_nop 1
	v_lshl_add_u64 v[56:57], v[120:121], 1, vcc
	global_load_dword v139, v[56:57], off offset:1024
	s_and_b64 vcc, exec, s[12:13]
	s_cbranch_vccz .LBB0_194

; __device__ __forceinline__ void pc_pass(int Q, const bf16* UG, bf16* A2, const float* cw, const float* cbias, LAS float* Yw, int mt, int ts, int lane) {
;     ...
;     for (int i = 0; i < 38; ++i) { const int t = ts - 30 + i; graw[i] = (t >= 0) ? __builtin_nontemporal_load((const unsigned*)(UG + (size_t)(mt - 30 + i) * 1024 + 512 + c0)) : 0u; }
.LBB0_174:
	v_readlane_b32 vcc_lo, v254, 43
	v_readlane_b32 vcc_hi, v254, 44
	s_nop 1
	v_lshl_add_u64 v[56:57], v[120:121], 1, vcc
	global_load_dword v136, v[56:57], off offset:1024
	s_and_b64 vcc, exec, s[12:13]
	s_cbranch_vccz .LBB0_196

; __device__ __forceinline__ void pc_pass(int Q, const bf16* UG, bf16* A2, const float* cw, const float* cbias, LAS float* Yw, int mt, int ts, int lane) {
;     ...
;     for (int i = 0; i < 38; ++i) { const int t = ts - 30 + i; graw[i] = (t >= 0) ? __builtin_nontemporal_load((const unsigned*)(UG + (size_t)(mt - 30 + i) * 1024 + 512 + c0)) : 0u; }
.LBB0_176:
	v_readlane_b32 vcc_lo, v254, 51
	v_readlane_b32 vcc_hi, v254, 52
	s_nop 1
	v_lshl_add_u64 v[56:57], v[120:121], 1, vcc
	global_load_dword v140, v[56:57], off offset:1024
	s_and_b64 vcc, exec, s[12:13]
	s_cbranch_vccz .LBB0_198

; __device__ __forceinline__ void pc_pass(int Q, const bf16* UG, bf16* A2, const float* cw, const float* cbias, LAS float* Yw, int mt, int ts, int lane) {
;     ...
;     for (int i = 0; i < 38; ++i) { const int t = ts - 30 + i; graw[i] = (t >= 0) ? __builtin_nontemporal_load((const unsigned*)(UG + (size_t)(mt - 30 + i) * 1024 + 512 + c0)) : 0u; }
.LBB0_178:
	v_readlane_b32 vcc_lo, v254, 59
	v_readlane_b32 vcc_hi, v254, 60
	s_nop 1
	v_lshl_add_u64 v[56:57], v[120:121], 1, vcc
	global_load_dword v162, v[56:57], off offset:1024
	s_and_b64 vcc, exec, s[12:13]
	s_cbranch_vccz .LBB0_200
	s_branch .LBB0_201

; __device__ __forceinline__ void pc_pass(int Q, const bf16* UG, bf16* A2, const float* cw, const float* cbias, LAS float* Yw, int mt, int ts, int lane) {
;     ...
;     for (int i = 0; i < 38; ++i) { const int t = ts - 30 + i; graw[i] = (t >= 0) ? __builtin_nontemporal_load((const unsigned*)(UG + (size_t)(mt - 30 + i) * 1024 + 512 + c0)) : 0u; }
.LBB0_180:
	v_readlane_b32 s12, v253, 43
	v_readlane_b32 s13, v253, 44
	s_nop 1
	v_lshl_add_u64 v[56:57], v[120:121], 1, s[12:13]
	global_load_dword v214, v[56:57], off offset:1024
	s_andn2_b64 vcc, exec, s[52:53]
	s_cbranch_vccz .LBB0_146

; __device__ __forceinline__ void pc_pass(int Q, const bf16* UG, bf16* A2, const float* cw, const float* cbias, LAS float* Yw, int mt, int ts, int lane) {
;     ...
;     for (int i = 0; i < 38; ++i) { const int t = ts - 30 + i; graw[i] = (t >= 0) ? __builtin_nontemporal_load((const unsigned*)(UG + (size_t)(mt - 30 + i) * 1024 + 512 + c0)) : 0u; }
.LBB0_182:
	v_readlane_b32 s12, v253, 47
	v_readlane_b32 s13, v253, 48
	s_nop 1
	v_lshl_add_u64 v[56:57], v[120:121], 1, s[12:13]
	global_load_dword v216, v[56:57], off offset:1024
	s_andn2_b64 vcc, exec, s[4:5]
	s_cbranch_vccz .LBB0_148

; __device__ __forceinline__ void pc_pass(int Q, const bf16* UG, bf16* A2, const float* cw, const float* cbias, LAS float* Yw, int mt, int ts, int lane) {
;     ...
;     for (int i = 0; i < 38; ++i) { const int t = ts - 30 + i; graw[i] = (t >= 0) ? __builtin_nontemporal_load((const unsigned*)(UG + (size_t)(mt - 30 + i) * 1024 + 512 + c0)) : 0u; }
.LBB0_184:
	v_readlane_b32 s12, v253, 51
	v_readlane_b32 s13, v253, 52
	s_nop 1
	v_lshl_add_u64 v[56:57], v[120:121], 1, s[12:13]
	global_load_dword v218, v[56:57], off offset:1024
	s_andn2_b64 vcc, exec, s[10:11]
	s_cbranch_vccz .LBB0_150

; __device__ __forceinline__ void pc_pass(int Q, const bf16* UG, bf16* A2, const float* cw, const float* cbias, LAS float* Yw, int mt, int ts, int lane) {
;     ...
;     for (int i = 0; i < 38; ++i) { const int t = ts - 30 + i; graw[i] = (t >= 0) ? __builtin_nontemporal_load((const unsigned*)(UG + (size_t)(mt - 30 + i) * 1024 + 512 + c0)) : 0u; }
.LBB0_186:
	v_readlane_b32 s12, v253, 55
	v_readlane_b32 s13, v253, 56
	s_nop 1
	v_lshl_add_u64 v[56:57], v[120:121], 1, s[12:13]
	global_load_dword v189, v[56:57], off offset:1024
	s_andn2_b64 vcc, exec, s[90:91]
	s_cbranch_vccz .LBB0_152

; __device__ __forceinline__ void pc_pass(int Q, const bf16* UG, bf16* A2, const float* cw, const float* cbias, LAS float* Yw, int mt, int ts, int lane) {
;     ...
;     for (int i = 0; i < 38; ++i) { const int t = ts - 30 + i; graw[i] = (t >= 0) ? __builtin_nontemporal_load((const unsigned*)(UG + (size_t)(mt - 30 + i) * 1024 + 512 + c0)) : 0u; }
.LBB0_188:
	v_readlane_b32 s12, v253, 59
	v_readlane_b32 s13, v253, 60
	s_nop 1
	v_lshl_add_u64 v[56:57], v[120:121], 1, s[12:13]
	global_load_dword v185, v[56:57], off offset:1024
	s_andn2_b64 vcc, exec, s[80:81]
	s_cbranch_vccz .LBB0_154

; __device__ __forceinline__ void pc_pass(int Q, const bf16* UG, bf16* A2, const float* cw, const float* cbias, LAS float* Yw, int mt, int ts, int lane) {
;     ...
;     for (int i = 0; i < 38; ++i) { const int t = ts - 30 + i; graw[i] = (t >= 0) ? __builtin_nontemporal_load((const unsigned*)(UG + (size_t)(mt - 30 + i) * 1024 + 512 + c0)) : 0u; }
.LBB0_190:
	v_readlane_b32 s12, v253, 63
	v_readlane_b32 s13, v254, 0
	s_nop 1
	v_lshl_add_u64 v[56:57], v[120:121], 1, s[12:13]
	global_load_dword v179, v[56:57], off offset:1024
	s_andn2_b64 vcc, exec, s[86:87]
	s_cbranch_vccz .LBB0_156

; __device__ __forceinline__ void pc_pass(int Q, const bf16* UG, bf16* A2, const float* cw, const float* cbias, LAS float* Yw, int mt, int ts, int lane) {
;     ...
;     for (int i = 0; i < 38; ++i) { const int t = ts - 30 + i; graw[i] = (t >= 0) ? __builtin_nontemporal_load((const unsigned*)(UG + (size_t)(mt - 30 + i) * 1024 + 512 + c0)) : 0u; }
.LBB0_192:
	v_readlane_b32 s12, v254, 3
	v_readlane_b32 s13, v254, 4
	s_nop 1
	v_lshl_add_u64 v[56:57], v[120:121], 1, s[12:13]
	global_load_dword v175, v[56:57], off offset:1024
	v_cndmask_b32_e64 v56, 0, 1, s[60:61]
	v_cmp_ne_u32_e64 s[14:15], 1, v56
	s_andn2_b64 vcc, exec, s[60:61]
	s_cbranch_vccz .LBB0_158
	s_branch .LBB0_159

; __device__ __forceinline__ void pc_pass(int Q, const bf16* UG, bf16* A2, const float* cw, const float* cbias, LAS float* Yw, int mt, int ts, int lane) {
;     ...
;     for (int i = 0; i < 38; ++i) { const int t = ts - 30 + i; graw[i] = (t >= 0) ? __builtin_nontemporal_load((const unsigned*)(UG + (size_t)(mt - 30 + i) * 1024 + 512 + c0)) : 0u; }
.LBB0_194:
	v_readlane_b32 vcc_lo, v254, 39
	v_readlane_b32 vcc_hi, v254, 40
	s_nop 1
	v_lshl_add_u64 v[56:57], v[120:121], 1, vcc
	global_load_dword v137, v[56:57], off offset:1024
	v_mov_b32_e32 v138, 0
	s_and_b64 vcc, exec, s[12:13]
	v_mov_b32_e32 v136, 0
	s_cbranch_vccz .LBB0_174

; __device__ __forceinline__ void pc_pass(int Q, const bf16* UG, bf16* A2, const float* cw, const float* cbias, LAS float* Yw, int mt, int ts, int lane) {
;     ...
;     for (int i = 0; i < 38; ++i) { const int t = ts - 30 + i; graw[i] = (t >= 0) ? __builtin_nontemporal_load((const unsigned*)(UG + (size_t)(mt - 30 + i) * 1024 + 512 + c0)) : 0u; }
.LBB0_196:
	v_readlane_b32 vcc_lo, v254, 47
	v_readlane_b32 vcc_hi, v254, 48
	s_nop 1
	v_lshl_add_u64 v[56:57], v[120:121], 1, vcc
	global_load_dword v138, v[56:57], off offset:1024
	v_mov_b32_e32 v142, 0
	s_and_b64 vcc, exec, s[12:13]
	v_mov_b32_e32 v140, 0
	s_cbranch_vccz .LBB0_176

; __device__ __forceinline__ void pc_pass(int Q, const bf16* UG, bf16* A2, const float* cw, const float* cbias, LAS float* Yw, int mt, int ts, int lane) {
;     ...
;     for (int i = 0; i < 38; ++i) { const int t = ts - 30 + i; graw[i] = (t >= 0) ? __builtin_nontemporal_load((const unsigned*)(UG + (size_t)(mt - 30 + i) * 1024 + 512 + c0)) : 0u; }
.LBB0_198:
	v_readlane_b32 vcc_lo, v254, 55
	v_readlane_b32 vcc_hi, v254, 56
	s_nop 1
	v_lshl_add_u64 v[56:57], v[120:121], 1, vcc
	global_load_dword v142, v[56:57], off offset:1024
	v_mov_b32_e32 v164, 0
	s_and_b64 vcc, exec, s[12:13]
	v_mov_b32_e32 v162, 0
	s_cbranch_vccz .LBB0_178

; __device__ __forceinline__ void pc_pass(int Q, const bf16* UG, bf16* A2, const float* cw, const float* cbias, LAS float* Yw, int mt, int ts, int lane) {
;     ...
;     for (int i = 0; i < 38; ++i) { const int t = ts - 30 + i; graw[i] = (t >= 0) ? __builtin_nontemporal_load((const unsigned*)(UG + (size_t)(mt - 30 + i) * 1024 + 512 + c0)) : 0u; }
; #pragma unroll
;     for (int i = 0; i < 23; ++i) { const int t = ts - 15 + i; uraw[i] = (t >= 0) ? __builtin_nontemporal_load((const unsigned*)(UG + (size_t)(mt - 15 + i) * 1024 + c0)) : 0u; }
.LBB0_200:
	v_readlane_b32 vcc_lo, v254, 63
	v_readlane_b32 vcc_hi, v255, 0
	s_nop 1
	v_lshl_add_u64 v[56:57], v[120:121], 1, vcc
	global_load_dword v164, v[56:57], off offset:1024
.LBB0_201:
	v_lshlrev_b64 v[56:57], 1, v[120:121]
	v_lshl_add_u64 v[58:59], s[68:69], 0, v[56:57]
	global_load_dword v168, v[58:59], off offset:1024
	v_lshl_add_u64 v[58:59], s[84:85], 0, v[56:57]
	global_load_dword v170, v[58:59], off offset:1024
	v_lshl_add_u64 v[58:59], s[28:29], 0, v[56:57]
	global_load_dword v167, v[58:59], off offset:1024
	v_lshl_add_u64 v[58:59], s[2:3], 0, v[56:57]
	global_load_dword v166, v[58:59], off offset:1024
	v_lshl_add_u64 v[58:59], s[62:63], 0, v[56:57]
	global_load_dword v172, v[58:59], off offset:1024
	v_lshl_add_u64 v[58:59], s[74:75], 0, v[56:57]
	global_load_dword v174, v[58:59], off offset:1024
	v_lshl_add_u64 v[58:59], s[88:89], 0, v[56:57]
	global_load_dword v176, v[58:59], off offset:1024
	v_lshl_add_u64 v[58:59], s[38:39], 0, v[56:57]
	global_load_dword v178, v[58:59], off offset:1024
	v_lshl_add_u64 v[56:57], s[40:41], 0, v[56:57]
	v_mov_b32_e32 v222, 0
	s_and_b64 vcc, exec, s[14:15]
	v_mov_b32_e32 v221, 0
	s_cbranch_vccnz .LBB0_229
	v_readlane_b32 s14, v254, 5
	v_readlane_b32 s15, v254, 6
	s_nop 1
	v_lshl_add_u64 v[58:59], v[56:57], 0, s[14:15]
	global_load_dword v221, v[58:59], off
	s_and_b64 vcc, exec, s[16:17]
	s_cbranch_vccz .LBB0_230

; __device__ __forceinline__ void pc_pass(int Q, const bf16* UG, bf16* A2, const float* cw, const float* cbias, LAS float* Yw, int mt, int ts, int lane) {
;     ...
;     for (int i = 0; i < 23; ++i) { const int t = ts - 15 + i; uraw[i] = (t >= 0) ? __builtin_nontemporal_load((const unsigned*)(UG + (size_t)(mt - 15 + i) * 1024 + c0)) : 0u; }
.LBB0_204:
	v_readlane_b32 s14, v254, 13
	v_readlane_b32 s15, v254, 14
	s_nop 1
	v_lshl_add_u64 v[58:59], v[56:57], 0, s[14:15]
	global_load_dword v223, v[58:59], off
	s_and_b64 vcc, exec, s[20:21]
	s_cbranch_vccz .LBB0_232

; __device__ __forceinline__ void pc_pass(int Q, const bf16* UG, bf16* A2, const float* cw, const float* cbias, LAS float* Yw, int mt, int ts, int lane) {
;     ...
;     for (int i = 0; i < 23; ++i) { const int t = ts - 15 + i; uraw[i] = (t >= 0) ? __builtin_nontemporal_load((const unsigned*)(UG + (size_t)(mt - 15 + i) * 1024 + c0)) : 0u; }
.LBB0_206:
	v_readlane_b32 s14, v254, 21
	v_readlane_b32 s15, v254, 22
	s_nop 1
	v_lshl_add_u64 v[58:59], v[56:57], 0, s[14:15]
	global_load_dword v225, v[58:59], off
	s_and_b64 vcc, exec, s[24:25]
	s_cbranch_vccz .LBB0_234

; __device__ __forceinline__ void pc_pass(int Q, const bf16* UG, bf16* A2, const float* cw, const float* cbias, LAS float* Yw, int mt, int ts, int lane) {
;     ...
;     for (int i = 0; i < 23; ++i) { const int t = ts - 15 + i; uraw[i] = (t >= 0) ? __builtin_nontemporal_load((const unsigned*)(UG + (size_t)(mt - 15 + i) * 1024 + c0)) : 0u; }
.LBB0_208:
	v_readlane_b32 s14, v254, 29
	v_readlane_b32 s15, v254, 30
	s_nop 1
	v_lshl_add_u64 v[58:59], v[56:57], 0, s[14:15]
	global_load_dword v227, v[58:59], off
	s_and_b64 vcc, exec, s[12:13]
	s_cbranch_vccz .LBB0_236

; __device__ __forceinline__ void pc_pass(int Q, const bf16* UG, bf16* A2, const float* cw, const float* cbias, LAS float* Yw, int mt, int ts, int lane) {
;     ...
;     for (int i = 0; i < 23; ++i) { const int t = ts - 15 + i; uraw[i] = (t >= 0) ? __builtin_nontemporal_load((const unsigned*)(UG + (size_t)(mt - 15 + i) * 1024 + c0)) : 0u; }
.LBB0_210:
	v_readlane_b32 s14, v254, 37
	v_readlane_b32 s15, v254, 38
	s_nop 1
	v_lshl_add_u64 v[58:59], v[56:57], 0, s[14:15]
	global_load_dword v135, v[58:59], off
	s_and_b64 vcc, exec, s[12:13]
	s_cbranch_vccz .LBB0_238

; __device__ __forceinline__ void pc_pass(int Q, const bf16* UG, bf16* A2, const float* cw, const float* cbias, LAS float* Yw, int mt, int ts, int lane) {
;     ...
;     for (int i = 0; i < 23; ++i) { const int t = ts - 15 + i; uraw[i] = (t >= 0) ? __builtin_nontemporal_load((const unsigned*)(UG + (size_t)(mt - 15 + i) * 1024 + c0)) : 0u; }
.LBB0_212:
	v_readlane_b32 s14, v254, 45
	v_readlane_b32 s15, v254, 46
	s_nop 1
	v_lshl_add_u64 v[58:59], v[56:57], 0, s[14:15]
	global_load_dword v131, v[58:59], off
	s_and_b64 vcc, exec, s[12:13]
	s_cbranch_vccz .LBB0_240

; __device__ __forceinline__ void pc_pass(int Q, const bf16* UG, bf16* A2, const float* cw, const float* cbias, LAS float* Yw, int mt, int ts, int lane) {
;     ...
;     for (int i = 0; i < 23; ++i) { const int t = ts - 15 + i; uraw[i] = (t >= 0) ? __builtin_nontemporal_load((const unsigned*)(UG + (size_t)(mt - 15 + i) * 1024 + c0)) : 0u; }
.LBB0_214:
	v_readlane_b32 s14, v254, 53
	v_readlane_b32 s15, v254, 54
	s_nop 1
	v_lshl_add_u64 v[58:59], v[56:57], 0, s[14:15]
	global_load_dword v219, v[58:59], off
	s_and_b64 vcc, exec, s[12:13]
	s_cbranch_vccz .LBB0_242

; #define PC_POOL(WIN) do { _Pragma("unroll") for (int t = 0; t < 8; ++t) { const f32x2 ut = bf2x2(uraw[15 + t]); f32x2 s = ut; _Pragma("unroll") for (int j = 1; j < WIN; ++j) s += bf2x2(uraw[15 + t - j]); \
;         const int cnt = min(ts + t + 1, WIN); const f32x2 p = s * __builtin_amdgcn_rcpf((float)cnt) - ut; *(unsigned*)(A2 + (size_t)(mt + t) * 1024 + c0) = pk2(p.x, p.y); } } while (0)
; __device__ __forceinline__ void pc_pass(int Q, const bf16* UG, bf16* A2, const float* cw, const float* cbias, LAS float* Yw, int mt, int ts, int lane) {
;     ...
;     for (int i = 0; i < 23; ++i) { const int t = ts - 15 + i; uraw[i] = (t >= 0) ? __builtin_nontemporal_load((const unsigned*)(UG + (size_t)(mt - 15 + i) * 1024 + c0)) : 0u; }
; #pragma unroll
;     for (int j = 0; j < 31; ++j) w[j] = *(const f32x2*)(cw + j * 512 + c0);
;     const f32x2 cb = *(const f32x2*)(cbias + c0);
;     ...
;     if (Q == 0) PC_POOL(2); else if (Q == 1) PC_POOL(4); else if (Q == 2) PC_POOL(8); else PC_POOL(16);
.LBB0_216:
	v_readlane_b32 s12, v254, 61
	v_readlane_b32 s13, v254, 62
	s_nop 1
	v_lshl_add_u64 v[58:59], v[56:57], 0, s[12:13]
	global_load_dword v124, v[58:59], off
.LBB0_217:
	v_readlane_b32 s12, v253, 23
	v_lshlrev_b64 v[118:119], 2, v[120:121]
	v_readlane_b32 s13, v253, 24
	v_lshl_add_u64 v[58:59], v[56:57], 0, s[34:35]
	v_lshl_add_u64 v[64:65], v[56:57], 0, s[78:79]
	v_lshl_add_u64 v[114:115], s[12:13], 0, v[118:119]
	s_movk_i32 s12, 0x1000
	v_lshl_add_u64 v[60:61], v[56:57], 0, s[76:77]
	v_lshl_add_u64 v[62:63], v[56:57], 0, s[66:67]
	v_lshl_add_u64 v[66:67], v[56:57], 0, s[70:71]
	v_lshl_add_u64 v[68:69], v[56:57], 0, s[64:65]
	v_lshl_add_u64 v[70:71], v[56:57], 0, s[30:31]
	v_lshl_add_u64 v[56:57], v[56:57], 0, s[36:37]
	global_load_dword v125, v[58:59], off
	global_load_dword v190, v[60:61], off
	global_load_dword v188, v[62:63], off
	global_load_dword v186, v[64:65], off
	global_load_dword v184, v[66:67], off
	global_load_dword v182, v[68:69], off
	global_load_dword v181, v[70:71], off
	global_load_dword v180, v[56:57], off
	v_add_co_u32_e32 v64, vcc, s12, v114
	s_movk_i32 s12, 0x2000
	s_nop 0
	v_addc_co_u32_e32 v65, vcc, 0, v115, vcc
	v_add_co_u32_e32 v58, vcc, s12, v114
	s_movk_i32 s12, 0x3000
	s_nop 0
	v_addc_co_u32_e32 v59, vcc, 0, v115, vcc
	v_add_co_u32_e32 v72, vcc, s12, v114
	s_movk_i32 s12, 0x4000
	s_nop 0
	v_addc_co_u32_e32 v73, vcc, 0, v115, vcc
	v_add_co_u32_e32 v74, vcc, s12, v114
	s_movk_i32 s12, 0x5000
	s_nop 0
	v_addc_co_u32_e32 v75, vcc, 0, v115, vcc
	v_add_co_u32_e32 v96, vcc, s12, v114
	s_movk_i32 s12, 0x6000
	s_nop 0
	v_addc_co_u32_e32 v97, vcc, 0, v115, vcc
	v_add_co_u32_e32 v80, vcc, s12, v114
	s_movk_i32 s12, 0x7000
	s_nop 0
	v_addc_co_u32_e32 v81, vcc, 0, v115, vcc
	v_add_co_u32_e32 v98, vcc, s12, v114
	s_mov_b32 s12, 0x8000
	s_nop 0
	v_addc_co_u32_e32 v99, vcc, 0, v115, vcc
	v_add_co_u32_e32 v86, vcc, s12, v114
	s_mov_b32 s12, 0x9000
	s_nop 0
	v_addc_co_u32_e32 v87, vcc, 0, v115, vcc
	v_add_co_u32_e32 v104, vcc, s12, v114
	s_mov_b32 s12, 0xa000
	s_nop 0
	v_addc_co_u32_e32 v105, vcc, 0, v115, vcc
	v_add_co_u32_e32 v90, vcc, s12, v114
	s_mov_b32 s12, 0xb000
	s_nop 0
	v_addc_co_u32_e32 v91, vcc, 0, v115, vcc
	v_add_co_u32_e32 v106, vcc, s12, v114
	s_mov_b32 s12, 0xc000
	s_nop 0
	v_addc_co_u32_e32 v107, vcc, 0, v115, vcc
	v_add_co_u32_e32 v108, vcc, s12, v114
	s_mov_b32 s12, 0xd000
	s_nop 0
	v_addc_co_u32_e32 v109, vcc, 0, v115, vcc
	v_add_co_u32_e32 v116, vcc, s12, v114
	global_load_dwordx2 v[60:61], v[58:59], off offset:-4096
	global_load_dwordx2 v[56:57], v[58:59], off
	s_nop 0
	global_load_dwordx2 v[58:59], v[58:59], off offset:2048
	s_nop 0
	global_load_dwordx2 v[62:63], v[74:75], off offset:-4096
	global_load_dwordx2 v[68:69], v[114:115], off
	global_load_dwordx2 v[70:71], v[114:115], off offset:2048
	global_load_dwordx2 v[66:67], v[64:65], off offset:2048
	s_nop 0
	global_load_dwordx2 v[64:65], v[72:73], off offset:2048
	s_nop 0
	global_load_dwordx2 v[72:73], v[74:75], off
	s_nop 0
	global_load_dwordx2 v[74:75], v[74:75], off offset:2048
	s_nop 0
	global_load_dwordx2 v[76:77], v[80:81], off offset:-4096
	global_load_dwordx2 v[78:79], v[80:81], off
	s_nop 0
	global_load_dwordx2 v[80:81], v[80:81], off offset:2048
	s_nop 0
	global_load_dwordx2 v[82:83], v[86:87], off offset:-4096
	global_load_dwordx2 v[84:85], v[86:87], off
	s_nop 0
	global_load_dwordx2 v[86:87], v[86:87], off offset:2048
	s_nop 0
	global_load_dwordx2 v[92:93], v[90:91], off offset:-4096
	global_load_dwordx2 v[88:89], v[90:91], off
	s_nop 0
	global_load_dwordx2 v[90:91], v[90:91], off offset:2048
	s_nop 0
	global_load_dwordx2 v[94:95], v[108:109], off offset:-4096
	global_load_dwordx2 v[102:103], v[96:97], off offset:2048
	global_load_dwordx2 v[100:101], v[98:99], off offset:2048
	s_nop 0
	global_load_dwordx2 v[98:99], v[104:105], off offset:2048
	global_load_dwordx2 v[96:97], v[106:107], off offset:2048
	v_addc_co_u32_e32 v117, vcc, 0, v115, vcc
	s_mov_b32 s12, 0xe000
	v_add_co_u32_e32 v112, vcc, s12, v114
	v_readlane_b32 s14, v253, 25
	s_nop 0
	v_addc_co_u32_e32 v113, vcc, 0, v115, vcc
	global_load_dwordx2 v[104:105], v[108:109], off
	global_load_dwordx2 v[106:107], v[108:109], off offset:2048
	s_nop 0
	global_load_dwordx2 v[108:109], v[112:113], off offset:-4096
	global_load_dwordx2 v[110:111], v[112:113], off
	s_nop 0
	global_load_dwordx2 v[112:113], v[112:113], off offset:2048
	v_readlane_b32 s15, v253, 26
	s_mov_b32 s12, 0xf000
	v_add_co_u32_e32 v122, vcc, s12, v114
	v_lshl_add_u64 v[118:119], s[14:15], 0, v[118:119]
	s_nop 0
	v_addc_co_u32_e32 v123, vcc, 0, v115, vcc
	global_load_dwordx2 v[114:115], v[116:117], off offset:2048
	s_nop 0
	global_load_dwordx2 v[116:117], v[122:123], off
	v_readlane_b32 s12, v253, 31
	global_load_dwordx2 v[118:119], v[118:119], off
	v_readlane_b32 s13, v253, 32
	s_waitcnt vmcnt(39)
	v_lshlrev_b32_e32 v122, 16, v125
	v_and_b32_e32 v123, 0xffff0000, v125
	v_lshlrev_b32_e32 v126, 16, v124
	v_and_b32_e32 v127, 0xffff0000, v124
	v_lshl_add_u64 v[120:121], v[120:121], 1, s[12:13]
	v_pk_add_f32 v[124:125], v[126:127], v[122:123]
	s_cmp_lt_i32 s51, 1
	s_mov_b64 s[12:13], -1
	v_readlane_b32 s16, v253, 27
	v_readlane_b32 s17, v253, 28
	v_readlane_b32 s18, v253, 29
	v_readlane_b32 s19, v253, 30
	s_cbranch_scc1 .LBB0_227
	s_cmp_lt_i32 s51, 2
	s_cbranch_scc1 .LBB0_224
	s_cmp_lg_u32 s51, 2
	v_lshlrev_b32_e32 v128, 16, v129
	v_and_b32_e32 v129, 0xffff0000, v129
	v_lshlrev_b32_e32 v130, 16, v131
	v_and_b32_e32 v131, 0xffff0000, v131
	v_lshlrev_b32_e32 v132, 16, v133
	v_and_b32_e32 v133, 0xffff0000, v133
	v_lshlrev_b32_e32 v134, 16, v135
	v_and_b32_e32 v135, 0xffff0000, v135
	s_cbranch_scc0 .LBB0_221
; #define PC_POOL(WIN) do { _Pragma("unroll") for (int t = 0; t < 8; ++t) { const f32x2 ut = bf2x2(uraw[15 + t]); f32x2 s = ut; _Pragma("unroll") for (int j = 1; j < WIN; ++j) s += bf2x2(uraw[15 + t - j]); \
;         const int cnt = min(ts + t + 1, WIN); const f32x2 p = s * __builtin_amdgcn_rcpf((float)cnt) - ut; *(unsigned*)(A2 + (size_t)(mt + t) * 1024 + c0) = pk2(p.x, p.y); } } while (0)
; __device__ __forceinline__ void pc_pass(int Q, const bf16* UG, bf16* A2, const float* cw, const float* cbias, LAS float* Yw, int mt, int ts, int lane) {
;     ...
;     if (Q == 0) PC_POOL(2); else if (Q == 1) PC_POOL(4); else if (Q == 2) PC_POOL(8); else PC_POOL(16);
	v_lshlrev_b32_e32 v208, 16, v220
	v_and_b32_e32 v209, 0xffff0000, v220
	v_pk_add_f32 v[230:231], v[124:125], v[208:209]
	v_lshlrev_b32_e32 v232, 16, v219
	v_and_b32_e32 v233, 0xffff0000, v219
	v_pk_add_f32 v[230:231], v[230:231], v[232:233]
	v_lshlrev_b32_e32 v234, 16, v228
	v_pk_add_f32 v[230:231], v[230:231], v[128:129]
	v_and_b32_e32 v235, 0xffff0000, v228
	v_pk_add_f32 v[230:231], v[230:231], v[130:131]
	v_lshlrev_b32_e32 v236, 16, v226
	v_pk_add_f32 v[230:231], v[230:231], v[132:133]
	v_and_b32_e32 v237, 0xffff0000, v226
	v_pk_add_f32 v[230:231], v[230:231], v[134:135]
	v_lshlrev_b32_e32 v238, 16, v224
	v_pk_add_f32 v[228:229], v[230:231], v[234:235]
	v_lshlrev_b32_e32 v230, 16, v227
	v_and_b32_e32 v231, 0xffff0000, v227
	v_pk_add_f32 v[228:229], v[228:229], v[230:231]
	v_and_b32_e32 v239, 0xffff0000, v224
	v_pk_add_f32 v[226:227], v[228:229], v[236:237]
	v_lshlrev_b32_e32 v228, 16, v225
	v_and_b32_e32 v229, 0xffff0000, v225
	v_pk_add_f32 v[226:227], v[226:227], v[228:229]
	v_lshlrev_b32_e32 v240, 16, v222
	v_pk_add_f32 v[224:225], v[226:227], v[238:239]
	v_lshlrev_b32_e32 v226, 16, v223
	v_and_b32_e32 v227, 0xffff0000, v223
	v_pk_add_f32 v[224:225], v[224:225], v[226:227]
	v_and_b32_e32 v241, 0xffff0000, v222
	v_pk_add_f32 v[222:223], v[224:225], v[240:241]
	v_lshlrev_b32_e32 v224, 16, v221
	v_and_b32_e32 v225, 0xffff0000, v221
	v_pk_add_f32 v[222:223], v[222:223], v[224:225]
	s_mov_b64 s[12:13], 0
	v_pk_fma_f32 v[222:223], v[40:41], v[222:223], v[122:123] neg_lo:[0,0,1] neg_hi:[0,0,1]
	s_nop 0
	v_cvt_pk_bf16_f32 v221, v222, v223
	v_lshl_add_u64 v[222:223], v[120:121], 0, s[34:35]
	global_store_dword v[222:223], v221, off
	s_waitcnt vmcnt(39)
	v_lshlrev_b32_e32 v222, 16, v190
	v_and_b32_e32 v223, 0xffff0000, v190
	v_pk_add_f32 v[224:225], v[122:123], v[222:223]
	s_nop 0
	v_pk_add_f32 v[224:225], v[224:225], v[126:127]
	s_nop 0
	v_pk_add_f32 v[224:225], v[224:225], v[208:209]
	s_nop 0
	v_pk_add_f32 v[224:225], v[224:225], v[232:233]
	s_nop 0
	v_pk_add_f32 v[224:225], v[224:225], v[128:129]
	s_nop 0
	v_pk_add_f32 v[224:225], v[224:225], v[130:131]
	s_nop 0
	v_pk_add_f32 v[224:225], v[224:225], v[132:133]
	s_nop 0
	v_pk_add_f32 v[224:225], v[224:225], v[134:135]
	s_nop 0
	v_pk_add_f32 v[224:225], v[224:225], v[234:235]
	s_nop 0
	v_pk_add_f32 v[224:225], v[224:225], v[230:231]
	s_nop 0
	v_pk_add_f32 v[224:225], v[224:225], v[236:237]
	s_nop 0
	v_pk_add_f32 v[224:225], v[224:225], v[228:229]
	s_nop 0
	v_pk_add_f32 v[224:225], v[224:225], v[238:239]
	s_nop 0
	v_pk_add_f32 v[224:225], v[224:225], v[226:227]
	s_nop 0
	v_pk_add_f32 v[224:225], v[224:225], v[240:241]
	s_nop 0
	v_pk_fma_f32 v[224:225], v[42:43], v[224:225], v[222:223] neg_lo:[0,0,1] neg_hi:[0,0,1]
	s_nop 0
	v_cvt_pk_bf16_f32 v221, v224, v225
	v_lshl_add_u64 v[224:225], v[120:121], 0, s[76:77]
	global_store_dword v[224:225], v221, off
	s_waitcnt vmcnt(39)
	v_lshlrev_b32_e32 v224, 16, v188
	v_and_b32_e32 v225, 0xffff0000, v188
	v_pk_add_f32 v[240:241], v[222:223], v[224:225]
	s_nop 0
	v_pk_add_f32 v[240:241], v[240:241], v[122:123]
	s_nop 0
	v_pk_add_f32 v[240:241], v[240:241], v[126:127]
	s_nop 0
	v_pk_add_f32 v[240:241], v[240:241], v[208:209]
	s_nop 0
	v_pk_add_f32 v[240:241], v[240:241], v[232:233]
	s_nop 0
	v_pk_add_f32 v[240:241], v[240:241], v[128:129]
	s_nop 0
	v_pk_add_f32 v[240:241], v[240:241], v[130:131]
	s_nop 0
	v_pk_add_f32 v[240:241], v[240:241], v[132:133]
	s_nop 0
	v_pk_add_f32 v[240:241], v[240:241], v[134:135]
	s_nop 0
	v_pk_add_f32 v[240:241], v[240:241], v[234:235]
	s_nop 0
	v_pk_add_f32 v[240:241], v[240:241], v[230:231]
	s_nop 0
	v_pk_add_f32 v[240:241], v[240:241], v[236:237]
	s_nop 0
	v_pk_add_f32 v[240:241], v[240:241], v[228:229]
	s_nop 0
	v_pk_add_f32 v[240:241], v[240:241], v[238:239]
	s_nop 0
	v_pk_add_f32 v[226:227], v[240:241], v[226:227]
	s_nop 0
	v_pk_fma_f32 v[226:227], v[44:45], v[226:227], v[224:225] neg_lo:[0,0,1] neg_hi:[0,0,1]
	s_nop 0
	v_cvt_pk_bf16_f32 v221, v226, v227
	v_lshl_add_u64 v[226:227], v[120:121], 0, s[66:67]
	global_store_dword v[226:227], v221, off
	s_waitcnt vmcnt(39)
	v_lshlrev_b32_e32 v226, 16, v186
	v_and_b32_e32 v227, 0xffff0000, v186
	v_pk_add_f32 v[240:241], v[224:225], v[226:227]
	s_nop 0
	v_pk_add_f32 v[240:241], v[240:241], v[222:223]
	s_nop 0
	v_pk_add_f32 v[240:241], v[240:241], v[122:123]
	s_nop 0
	v_pk_add_f32 v[240:241], v[240:241], v[126:127]
	s_nop 0
	v_pk_add_f32 v[240:241], v[240:241], v[208:209]
	s_nop 0
	v_pk_add_f32 v[240:241], v[240:241], v[232:233]
	s_nop 0
	v_pk_add_f32 v[240:241], v[240:241], v[128:129]
	s_nop 0
	v_pk_add_f32 v[240:241], v[240:241], v[130:131]
	s_nop 0
	v_pk_add_f32 v[240:241], v[240:241], v[132:133]
	s_nop 0
	v_pk_add_f32 v[240:241], v[240:241], v[134:135]
	s_nop 0
	v_pk_add_f32 v[240:241], v[240:241], v[234:235]
	s_nop 0
	v_pk_add_f32 v[240:241], v[240:241], v[230:231]
	s_nop 0
	v_pk_add_f32 v[240:241], v[240:241], v[236:237]
	s_nop 0
	v_pk_add_f32 v[240:241], v[240:241], v[228:229]
	s_nop 0
	v_pk_add_f32 v[238:239], v[240:241], v[238:239]
	s_nop 0
	v_pk_fma_f32 v[238:239], v[46:47], v[238:239], v[226:227] neg_lo:[0,0,1] neg_hi:[0,0,1]
	s_nop 0
	v_cvt_pk_bf16_f32 v221, v238, v239
	v_lshl_add_u64 v[238:239], v[120:121], 0, s[78:79]
	global_store_dword v[238:239], v221, off
	s_waitcnt vmcnt(39)
; #define PC_POOL(WIN) do { _Pragma("unroll") for (int t = 0; t < 8; ++t) { const f32x2 ut = bf2x2(uraw[15 + t]); f32x2 s = ut; _Pragma("unroll") for (int j = 1; j < WIN; ++j) s += bf2x2(uraw[15 + t - j]); \
;         const int cnt = min(ts + t + 1, WIN); const f32x2 p = s * __builtin_amdgcn_rcpf((float)cnt) - ut; *(unsigned*)(A2 + (size_t)(mt + t) * 1024 + c0) = pk2(p.x, p.y); } } while (0)
; __device__ __forceinline__ void pc_pass(int Q, const bf16* UG, bf16* A2, const float* cw, const float* cbias, LAS float* Yw, int mt, int ts, int lane) {
;     ...
;     if (Q == 0) PC_POOL(2); else if (Q == 1) PC_POOL(4); else if (Q == 2) PC_POOL(8); else PC_POOL(16);
	v_lshlrev_b32_e32 v238, 16, v184
	v_and_b32_e32 v239, 0xffff0000, v184
	v_pk_add_f32 v[240:241], v[226:227], v[238:239]
	s_nop 0
	v_pk_add_f32 v[240:241], v[240:241], v[224:225]
	s_nop 0
	v_pk_add_f32 v[240:241], v[240:241], v[222:223]
	s_nop 0
	v_pk_add_f32 v[240:241], v[240:241], v[122:123]
	s_nop 0
	v_pk_add_f32 v[240:241], v[240:241], v[126:127]
	s_nop 0
	v_pk_add_f32 v[240:241], v[240:241], v[208:209]
	s_nop 0
	v_pk_add_f32 v[240:241], v[240:241], v[232:233]
	s_nop 0
	v_pk_add_f32 v[240:241], v[240:241], v[128:129]
	s_nop 0
	v_pk_add_f32 v[240:241], v[240:241], v[130:131]
	s_nop 0
	v_pk_add_f32 v[240:241], v[240:241], v[132:133]
	s_nop 0
	v_pk_add_f32 v[240:241], v[240:241], v[134:135]
	s_nop 0
	v_pk_add_f32 v[240:241], v[240:241], v[234:235]
	s_nop 0
	v_pk_add_f32 v[240:241], v[240:241], v[230:231]
	s_nop 0
	v_pk_add_f32 v[240:241], v[240:241], v[236:237]
	s_nop 0
	v_pk_add_f32 v[228:229], v[240:241], v[228:229]
	s_nop 0
	v_pk_fma_f32 v[228:229], v[48:49], v[228:229], v[238:239] neg_lo:[0,0,1] neg_hi:[0,0,1]
	s_nop 0
	v_cvt_pk_bf16_f32 v221, v228, v229
	v_lshl_add_u64 v[228:229], v[120:121], 0, s[70:71]
	global_store_dword v[228:229], v221, off
	s_waitcnt vmcnt(39)
	v_lshlrev_b32_e32 v228, 16, v182
	v_and_b32_e32 v229, 0xffff0000, v182
	v_pk_add_f32 v[240:241], v[238:239], v[228:229]
	s_nop 0
	v_pk_add_f32 v[240:241], v[240:241], v[226:227]
	s_nop 0
	v_pk_add_f32 v[240:241], v[240:241], v[224:225]
	s_nop 0
	v_pk_add_f32 v[240:241], v[240:241], v[222:223]
	s_nop 0
	v_pk_add_f32 v[240:241], v[240:241], v[122:123]
	s_nop 0
	v_pk_add_f32 v[240:241], v[240:241], v[126:127]
	s_nop 0
	v_pk_add_f32 v[240:241], v[240:241], v[208:209]
	s_nop 0
	v_pk_add_f32 v[240:241], v[240:241], v[232:233]
	s_nop 0
	v_pk_add_f32 v[240:241], v[240:241], v[128:129]
	s_nop 0
	v_pk_add_f32 v[240:241], v[240:241], v[130:131]
	s_nop 0
	v_pk_add_f32 v[240:241], v[240:241], v[132:133]
	s_nop 0
	v_pk_add_f32 v[240:241], v[240:241], v[134:135]
	s_nop 0
	v_pk_add_f32 v[240:241], v[240:241], v[234:235]
	s_nop 0
	v_pk_add_f32 v[240:241], v[240:241], v[230:231]
	s_nop 0
	v_pk_add_f32 v[236:237], v[240:241], v[236:237]
	s_nop 0
	v_pk_fma_f32 v[236:237], v[50:51], v[236:237], v[228:229] neg_lo:[0,0,1] neg_hi:[0,0,1]
	s_nop 0
	v_cvt_pk_bf16_f32 v221, v236, v237
	v_lshl_add_u64 v[236:237], v[120:121], 0, s[64:65]
	global_store_dword v[236:237], v221, off
	s_waitcnt vmcnt(39)
	v_lshlrev_b32_e32 v236, 16, v181
	v_and_b32_e32 v237, 0xffff0000, v181
	v_pk_add_f32 v[240:241], v[228:229], v[236:237]
	s_nop 0
	v_pk_add_f32 v[240:241], v[240:241], v[238:239]
	s_nop 0
	v_pk_add_f32 v[240:241], v[240:241], v[226:227]
	s_nop 0
	v_pk_add_f32 v[240:241], v[240:241], v[224:225]
	s_nop 0
	v_pk_add_f32 v[240:241], v[240:241], v[222:223]
	s_nop 0
	v_pk_add_f32 v[240:241], v[240:241], v[122:123]
	s_nop 0
	v_pk_add_f32 v[240:241], v[240:241], v[126:127]
	s_nop 0
	v_pk_add_f32 v[240:241], v[240:241], v[208:209]
	s_nop 0
	v_pk_add_f32 v[240:241], v[240:241], v[232:233]
	s_nop 0
	v_pk_add_f32 v[240:241], v[240:241], v[128:129]
	s_nop 0
	v_pk_add_f32 v[240:241], v[240:241], v[130:131]
	s_nop 0
	v_pk_add_f32 v[240:241], v[240:241], v[132:133]
	s_nop 0
	v_pk_add_f32 v[240:241], v[240:241], v[134:135]
	s_nop 0
	v_pk_add_f32 v[240:241], v[240:241], v[234:235]
	s_nop 0
	v_pk_add_f32 v[230:231], v[240:241], v[230:231]
	s_nop 0
	v_pk_fma_f32 v[230:231], v[52:53], v[230:231], v[236:237] neg_lo:[0,0,1] neg_hi:[0,0,1]
	s_nop 0
	v_cvt_pk_bf16_f32 v221, v230, v231
	v_lshl_add_u64 v[230:231], v[120:121], 0, s[30:31]
	global_store_dword v[230:231], v221, off
	s_waitcnt vmcnt(39)
	v_lshlrev_b32_e32 v230, 16, v180
	v_and_b32_e32 v231, 0xffff0000, v180
	v_pk_add_f32 v[236:237], v[236:237], v[230:231]
	s_nop 0
	v_pk_add_f32 v[228:229], v[236:237], v[228:229]
	s_nop 0
	v_pk_add_f32 v[228:229], v[228:229], v[238:239]
	s_nop 0
	v_pk_add_f32 v[226:227], v[228:229], v[226:227]
	s_nop 0
	v_pk_add_f32 v[224:225], v[226:227], v[224:225]
	s_nop 0
	v_pk_add_f32 v[222:223], v[224:225], v[222:223]
	s_nop 0
	v_pk_add_f32 v[222:223], v[222:223], v[122:123]
	s_nop 0
	v_pk_add_f32 v[222:223], v[222:223], v[126:127]
	s_nop 0
	v_pk_add_f32 v[208:209], v[222:223], v[208:209]
	s_nop 0
	v_pk_add_f32 v[208:209], v[208:209], v[232:233]
	s_nop 0
	v_pk_add_f32 v[208:209], v[208:209], v[128:129]
	s_nop 0
	v_pk_add_f32 v[208:209], v[208:209], v[130:131]
	s_nop 0
	v_pk_add_f32 v[208:209], v[208:209], v[132:133]
	s_nop 0
	v_pk_add_f32 v[208:209], v[208:209], v[134:135]
	s_nop 0
	v_pk_add_f32 v[208:209], v[208:209], v[234:235]
	s_nop 0
	v_pk_fma_f32 v[208:209], v[54:55], v[208:209], v[230:231] neg_lo:[0,0,1] neg_hi:[0,0,1]
	s_nop 0
	v_cvt_pk_bf16_f32 v229, v208, v209

; __device__ __forceinline__ void pc_pass(int Q, const bf16* UG, bf16* A2, const float* cw, const float* cbias, LAS float* Yw, int mt, int ts, int lane) {
;     ...
;     for (int i = 0; i < 23; ++i) { const int t = ts - 15 + i; uraw[i] = (t >= 0) ? __builtin_nontemporal_load((const unsigned*)(UG + (size_t)(mt - 15 + i) * 1024 + c0)) : 0u; }
.LBB0_230:
	v_readlane_b32 s14, v254, 9
	v_readlane_b32 s15, v254, 10
	s_nop 1
	v_lshl_add_u64 v[58:59], v[56:57], 0, s[14:15]
	global_load_dword v222, v[58:59], off
	v_mov_b32_e32 v224, 0
	s_and_b64 vcc, exec, s[18:19]
	v_mov_b32_e32 v223, 0
	s_cbranch_vccz .LBB0_204

; __device__ __forceinline__ void pc_pass(int Q, const bf16* UG, bf16* A2, const float* cw, const float* cbias, LAS float* Yw, int mt, int ts, int lane) {
;     ...
;     for (int i = 0; i < 23; ++i) { const int t = ts - 15 + i; uraw[i] = (t >= 0) ? __builtin_nontemporal_load((const unsigned*)(UG + (size_t)(mt - 15 + i) * 1024 + c0)) : 0u; }
.LBB0_232:
	v_readlane_b32 s14, v254, 17
	v_readlane_b32 s15, v254, 18
	s_nop 1
	v_lshl_add_u64 v[58:59], v[56:57], 0, s[14:15]
	global_load_dword v224, v[58:59], off
	v_mov_b32_e32 v226, 0
	s_and_b64 vcc, exec, s[22:23]
	v_mov_b32_e32 v225, 0
	s_cbranch_vccz .LBB0_206

; __device__ __forceinline__ void pc_pass(int Q, const bf16* UG, bf16* A2, const float* cw, const float* cbias, LAS float* Yw, int mt, int ts, int lane) {
;     ...
;     for (int i = 0; i < 23; ++i) { const int t = ts - 15 + i; uraw[i] = (t >= 0) ? __builtin_nontemporal_load((const unsigned*)(UG + (size_t)(mt - 15 + i) * 1024 + c0)) : 0u; }
.LBB0_234:
	v_readlane_b32 s14, v254, 25
	v_readlane_b32 s15, v254, 26
	s_nop 1
	v_lshl_add_u64 v[58:59], v[56:57], 0, s[14:15]
	global_load_dword v226, v[58:59], off
	v_mov_b32_e32 v228, 0
	s_and_b64 vcc, exec, s[26:27]
	v_mov_b32_e32 v227, 0
	s_cbranch_vccz .LBB0_208

; __device__ __forceinline__ void pc_pass(int Q, const bf16* UG, bf16* A2, const float* cw, const float* cbias, LAS float* Yw, int mt, int ts, int lane) {
;     ...
;     for (int i = 0; i < 23; ++i) { const int t = ts - 15 + i; uraw[i] = (t >= 0) ? __builtin_nontemporal_load((const unsigned*)(UG + (size_t)(mt - 15 + i) * 1024 + c0)) : 0u; }
.LBB0_236:
	v_readlane_b32 s14, v254, 33
	v_readlane_b32 s15, v254, 34
	s_nop 1
	v_lshl_add_u64 v[58:59], v[56:57], 0, s[14:15]
	global_load_dword v228, v[58:59], off
	v_mov_b32_e32 v133, 0
	s_and_b64 vcc, exec, s[12:13]
	v_mov_b32_e32 v135, 0
	s_cbranch_vccz .LBB0_210

; __device__ __forceinline__ void pc_pass(int Q, const bf16* UG, bf16* A2, const float* cw, const float* cbias, LAS float* Yw, int mt, int ts, int lane) {
;     ...
;     for (int i = 0; i < 23; ++i) { const int t = ts - 15 + i; uraw[i] = (t >= 0) ? __builtin_nontemporal_load((const unsigned*)(UG + (size_t)(mt - 15 + i) * 1024 + c0)) : 0u; }
.LBB0_238:
	v_readlane_b32 s14, v254, 41
	v_readlane_b32 s15, v254, 42
	s_nop 1
	v_lshl_add_u64 v[58:59], v[56:57], 0, s[14:15]
	global_load_dword v133, v[58:59], off
	v_mov_b32_e32 v129, 0
	s_and_b64 vcc, exec, s[12:13]
	v_mov_b32_e32 v131, 0
	s_cbranch_vccz .LBB0_212

; __device__ __forceinline__ void pc_pass(int Q, const bf16* UG, bf16* A2, const float* cw, const float* cbias, LAS float* Yw, int mt, int ts, int lane) {
;     ...
;     for (int i = 0; i < 23; ++i) { const int t = ts - 15 + i; uraw[i] = (t >= 0) ? __builtin_nontemporal_load((const unsigned*)(UG + (size_t)(mt - 15 + i) * 1024 + c0)) : 0u; }
.LBB0_240:
	v_readlane_b32 s14, v254, 49
	v_readlane_b32 s15, v254, 50
	s_nop 1
	v_lshl_add_u64 v[58:59], v[56:57], 0, s[14:15]
	global_load_dword v129, v[58:59], off
	v_mov_b32_e32 v220, 0
	s_and_b64 vcc, exec, s[12:13]
	v_mov_b32_e32 v219, 0
	s_cbranch_vccz .LBB0_214

; __device__ __forceinline__ void pc_pass(int Q, const bf16* UG, bf16* A2, const float* cw, const float* cbias, LAS float* Yw, int mt, int ts, int lane) {
;     ...
;     for (int i = 0; i < 23; ++i) { const int t = ts - 15 + i; uraw[i] = (t >= 0) ? __builtin_nontemporal_load((const unsigned*)(UG + (size_t)(mt - 15 + i) * 1024 + c0)) : 0u; }
.LBB0_242:
	v_readlane_b32 s14, v254, 57
	v_readlane_b32 s15, v254, 58
	s_nop 1
	v_lshl_add_u64 v[58:59], v[56:57], 0, s[14:15]
	global_load_dword v220, v[58:59], off
	s_and_b64 vcc, exec, s[12:13]
	v_mov_b32_e32 v124, 0
	s_cbranch_vccz .LBB0_216
	s_branch .LBB0_217
